# attnA: the two Q fragment loads replaced by coalesced row loads + LDS fragment reads (staged with K chunk 0)
# speedup vs baseline: 1.0147x; 1.0059x over previous
; #define GAS __attribute__((address_space(1)))
; __device__ __forceinline__ void attnA_unit(const Ctx& C, int unit) {
;     ...
;         const int tq = r + dl * (i0 + i16);
;         const unsigned qoff = (unsigned)tq * (ZC * 2) + (QA + head * 64 + 8 * g) * 2;
;         const bf16x8 q0 = *(const GAS bf16x8*)(Zg + qoff), q1 = *(const GAS bf16x8*)(Zg + qoff + 64);
;         const int kbase = i0 - 144;
;         const int klane = kbase + 8 * (i16 >> 2) + (i16 & 3);
;         const unsigned kcol = rbase + (KA + head * 64 + 8 * g) * 2;
;         bf16x8 kf[10][2];
; #pragma unroll
;         for (int kt = 0; kt < 10; ++kt) { int ks = klane + 32 * (kt >> 1) + 4 * (kt & 1); ks = ks < 0 ? 0 : ks;
;             const unsigned off = (unsigned)ks * rstride + kcol; kf[kt][0] = *(const GAS bf16x8*)(Zg + off); kf[kt][1] = *(const GAS bf16x8*)(Zg + off + 64); }
;         v4u vreg[5][4];
;         { const int vl = kbase + (lane >> 3); const unsigned vcol = rbase + (VA + head * 64 + (lane & 7) * 8) * 2;
; #pragma unroll
;           for (int s5 = 0; s5 < 5; ++s5)
; #pragma unroll
;             for (int i = 0; i < 4; ++i) { int ks = vl + 32 * s5 + 8 * i; ks = ks < 0 ? 0 : ks; vreg[s5][i] = *(const GAS v4u*)(Zg + (unsigned)ks * rstride + vcol); } }
.LBB0_565:
	v_add_u32_e32 v0, s24, v133
	v_mul_lo_u32 v0, s25, v0
	s_lshl_b32 s68, s26, 8
	v_add_u32_e32 v145, s56, v0
	s_or_b32 s31, s68, s36
	v_mul_lo_u32 v0, v145, s33
	v_or_b32_e32 v1, s31, v134
	s_mul_i32 s27, s25, 0x2600
	v_lshl_add_u32 v0, v1, 1, v0
	s_add_i32 s25, s24, 0xffffff70
	s_mul_i32 s30, s56, 0x2600
	v_add_u32_e32 v2, s24, v139
	v_mul_lo_u32 v2, v2, s27
	v_add_u32_e32 v2, s30, v2
	v_and_b32_e32 v3, 0x70, v140
	v_add_u32_e32 v2, v2, v3
	s_lshl_b32 s28, s31, 1
	v_add_u32_e32 v2, s28, v2
	s_lshl_b32 s28, s27, 3
	global_load_dwordx4 v[84:87], v2, s[66:67]
	v_add_u32_e32 v3, s28, v2
	global_load_dwordx4 v[80:83], v3, s[66:67]
	s_lshl_b32 s28, s31, 1
	v_add_u32_e32 v12, s25, v139
	s_add_i32 s30, s30, s28
	v_add_u32_e32 v192, s30, v140
	v_lshl_add_u64 v[8:9], s[66:67], 0, v[192:193]
	v_max_i32_e32 v0, 0, v12
	v_mul_lo_u32 v192, v0, s27
	v_lshl_add_u64 v[0:1], v[8:9], 0, v[192:193]
	global_load_dwordx4 v[146:149], v[0:1], off offset:-1536
	v_max_i32_e32 v2, -8, v12
	v_add_u32_e32 v2, 8, v2
	v_mul_lo_u32 v192, v2, s27
	v_lshl_add_u64 v[2:3], v[8:9], 0, v[192:193]
	global_load_dwordx4 v[150:153], v[2:3], off offset:-1536
	v_max_i32_e32 v0, -16, v12
	v_add_u32_e32 v0, 16, v0
	v_mul_lo_u32 v192, v0, s27
	v_lshl_add_u64 v[0:1], v[8:9], 0, v[192:193]
	global_load_dwordx4 v[154:157], v[0:1], off offset:-1536
	v_max_i32_e32 v2, -24, v12
	v_add_u32_e32 v2, 24, v2
	v_mul_lo_u32 v192, v2, s27
	v_lshl_add_u64 v[2:3], v[8:9], 0, v[192:193]
	global_load_dwordx4 v[158:161], v[2:3], off offset:-1536
	v_max_i32_e32 v0, -32, v12
	v_add_u32_e32 v0, 32, v0
	v_mul_lo_u32 v192, v0, s27
	v_lshl_add_u64 v[0:1], v[8:9], 0, v[192:193]
	global_load_dwordx4 v[162:165], v[0:1], off offset:-1536
	v_max_i32_e32 v2, -40, v12
	v_add_u32_e32 v2, 40, v2
	v_mul_lo_u32 v192, v2, s27
	v_lshl_add_u64 v[2:3], v[8:9], 0, v[192:193]
	global_load_dwordx4 v[166:169], v[2:3], off offset:-1536
	v_max_i32_e32 v0, -48, v12
	v_add_u32_e32 v0, 48, v0
	v_mul_lo_u32 v192, v0, s27
	v_lshl_add_u64 v[0:1], v[8:9], 0, v[192:193]
	global_load_dwordx4 v[170:173], v[0:1], off offset:-1536
	v_max_i32_e32 v2, -56, v12
	v_add_u32_e32 v2, 56, v2
	v_mul_lo_u32 v192, v2, s27
	v_lshl_add_u64 v[2:3], v[8:9], 0, v[192:193]
	global_load_dwordx4 v[174:177], v[2:3], off offset:-1536
	v_max_i32_e32 v0, -64, v12
	v_add_u32_e32 v0, 64, v0
	v_mul_lo_u32 v192, v0, s27
	v_lshl_add_u64 v[0:1], v[8:9], 0, v[192:193]
	global_load_dwordx4 v[178:181], v[0:1], off offset:-1536
	v_max_i32_e32 v2, -72, v12
	v_add_u32_e32 v2, 72, v2
	v_mul_lo_u32 v192, v2, s27
	v_lshl_add_u64 v[2:3], v[8:9], 0, v[192:193]
	global_load_dwordx4 v[128:131], v[2:3], off offset:-1536
	v_max_i32_e32 v0, -80, v12
	v_add_u32_e32 v0, 80, v0
	v_mul_lo_u32 v192, v0, s27
	v_lshl_add_u64 v[0:1], v[8:9], 0, v[192:193]
	global_load_dwordx4 v[124:127], v[0:1], off offset:-1536
	v_max_i32_e32 v2, -88, v12
	v_add_u32_e32 v2, 88, v2
	v_mul_lo_u32 v192, v2, s27
	v_lshl_add_u64 v[2:3], v[8:9], 0, v[192:193]
	global_load_dwordx4 v[120:123], v[2:3], off offset:-1536
	v_max_i32_e32 v0, -96, v12
	v_add_u32_e32 v0, 96, v0
	v_mul_lo_u32 v192, v0, s27
	v_lshl_add_u64 v[0:1], v[8:9], 0, v[192:193]
	global_load_dwordx4 v[116:119], v[0:1], off offset:-1536
	v_max_i32_e32 v2, -104, v12
	v_add_u32_e32 v2, 104, v2
	v_mul_lo_u32 v192, v2, s27
	v_lshl_add_u64 v[2:3], v[8:9], 0, v[192:193]
	global_load_dwordx4 v[112:115], v[2:3], off offset:-1536
	v_max_i32_e32 v0, -112, v12
	v_add_u32_e32 v0, 112, v0
	v_mul_lo_u32 v192, v0, s27
	v_lshl_add_u64 v[0:1], v[8:9], 0, v[192:193]
	global_load_dwordx4 v[108:111], v[0:1], off offset:-1536
	v_max_i32_e32 v2, -120, v12
	v_add_u32_e32 v2, 120, v2
	v_mul_lo_u32 v192, v2, s27
	v_lshl_add_u64 v[2:3], v[8:9], 0, v[192:193]
	global_load_dwordx4 v[100:103], v[2:3], off offset:-1536
	v_max_i32_e32 v0, -128, v12
	v_add_u32_e32 v0, 128, v0
	v_mul_lo_u32 v192, v0, s27
	v_lshl_add_u64 v[0:1], v[8:9], 0, v[192:193]
	global_load_dwordx4 v[104:107], v[0:1], off offset:-1536
	v_max_i32_e32 v2, -136, v12
	v_add_u32_e32 v2, 136, v2
	v_mul_lo_u32 v192, v2, s27
	v_lshl_add_u64 v[2:3], v[8:9], 0, v[192:193]
	global_load_dwordx4 v[96:99], v[2:3], off offset:-1536
	v_max_i32_e32 v0, -144, v12
	v_add_u32_e32 v0, 144, v0
	v_mul_lo_u32 v192, v0, s27
	v_lshl_add_u64 v[0:1], v[8:9], 0, v[192:193]
	global_load_dwordx4 v[92:95], v[0:1], off offset:-1536
	v_max_i32_e32 v2, -152, v12
	v_add_u32_e32 v2, 152, v2
	v_mul_lo_u32 v192, v2, s27
	v_lshl_add_u64 v[2:3], v[8:9], 0, v[192:193]
	global_load_dwordx4 v[88:91], v[2:3], off offset:-1536
	v_add_u32_e32 v192, s30, v140
	v_max_i32_e32 v0, 0, v12
	v_max_i32_e32 v2, -8, v12
	v_lshl_add_u64 v[8:9], s[66:67], 0, v[192:193]
	v_mul_lo_u32 v192, v0, s27
	v_add_u32_e32 v2, 8, v2
	v_lshl_add_u64 v[0:1], v[8:9], 0, v[192:193]
	v_mul_lo_u32 v192, v2, s27
	v_lshl_add_u64 v[2:3], v[8:9], 0, v[192:193]
	global_load_dwordx4 v[64:67], v[0:1], off
	global_load_dwordx4 v[68:71], v[2:3], off
	v_max_i32_e32 v0, -16, v12
	v_add_u32_e32 v0, 16, v0
	v_max_i32_e32 v2, 0xffffffe8, v12
	v_mul_lo_u32 v192, v0, s27
	v_add_u32_e32 v2, 24, v2
	v_lshl_add_u64 v[0:1], v[8:9], 0, v[192:193]
	v_mul_lo_u32 v192, v2, s27
	v_lshl_add_u64 v[2:3], v[8:9], 0, v[192:193]
	global_load_dwordx4 v[72:75], v[0:1], off
	global_load_dwordx4 v[76:79], v[2:3], off
	v_max_i32_e32 v0, 0xffffffe0, v12
	v_add_u32_e32 v0, 32, v0
	v_max_i32_e32 v2, 0xffffffd8, v12
	v_mul_lo_u32 v192, v0, s27
	v_add_u32_e32 v2, 40, v2
	v_lshl_add_u64 v[0:1], v[8:9], 0, v[192:193]
	v_mul_lo_u32 v192, v2, s27
	v_lshl_add_u64 v[2:3], v[8:9], 0, v[192:193]
	global_load_dwordx4 v[48:51], v[0:1], off
	global_load_dwordx4 v[52:55], v[2:3], off
	v_max_i32_e32 v0, 0xffffffd0, v12
; #define GAS __attribute__((address_space(1)))
; __device__ __forceinline__ f32x4 mfma16(bf16x8 a, bf16x8 b, f32x4 c) { return __builtin_amdgcn_mfma_f32_16x16x32_bf16(a, b, c, 0, 0, 0); }
; #define SBAR() __builtin_amdgcn_sched_barrier(0)
; #define SBAR() __builtin_amdgcn_sched_barrier(0)
; __device__ __forceinline__ void attnA_unit(const Ctx& C, int unit) {
;     ...
;         bf16x8 kf[10][2];
; #pragma unroll
;         for (int kt = 0; kt < 10; ++kt) { int ks = klane + 32 * (kt >> 1) + 4 * (kt & 1); ks = ks < 0 ? 0 : ks;
;             const unsigned off = (unsigned)ks * rstride + kcol; kf[kt][0] = *(const GAS bf16x8*)(Zg + off); kf[kt][1] = *(const GAS bf16x8*)(Zg + off + 64); }
;         v4u vreg[5][4];
;         { const int vl = kbase + (lane >> 3); const unsigned vcol = rbase + (VA + head * 64 + (lane & 7) * 8) * 2;
; #pragma unroll
;           for (int s5 = 0; s5 < 5; ++s5)
; #pragma unroll
;             for (int i = 0; i < 4; ++i) { int ks = vl + 32 * s5 + 8 * i; ks = ks < 0 ? 0 : ks; vreg[s5][i] = *(const GAS v4u*)(Zg + (unsigned)ks * rstride + vcol); } }
;         SBAR();
;         f32x4 S[10];
; #pragma unroll
;         for (int kt = 0; kt < 10; ++kt) { f32x4 a = mfma16(kf[kt][0], q0, (f32x4){0.f, 0.f, 0.f, 0.f}); S[kt] = mfma16(kf[kt][1], q1, a); }
	v_add_u32_e32 v0, 48, v0
	v_max_i32_e32 v2, 0xffffffc8, v12
	v_mul_lo_u32 v192, v0, s27
	v_add_u32_e32 v2, 56, v2
	v_lshl_add_u64 v[0:1], v[8:9], 0, v[192:193]
	v_mul_lo_u32 v192, v2, s27
	v_lshl_add_u64 v[2:3], v[8:9], 0, v[192:193]
	global_load_dwordx4 v[56:59], v[0:1], off
	global_load_dwordx4 v[60:63], v[2:3], off
	v_max_i32_e32 v0, 0xffffffc0, v12
	v_add_u32_e32 v0, 64, v0
	v_max_i32_e32 v2, 0xffffffb8, v12
	v_mul_lo_u32 v192, v0, s27
	v_add_u32_e32 v2, 0x48, v2
	v_lshl_add_u64 v[0:1], v[8:9], 0, v[192:193]
	v_mul_lo_u32 v192, v2, s27
	v_lshl_add_u64 v[2:3], v[8:9], 0, v[192:193]
	global_load_dwordx4 v[32:35], v[0:1], off
	global_load_dwordx4 v[36:39], v[2:3], off
	v_max_i32_e32 v0, 0xffffffb0, v12
	v_add_u32_e32 v0, 0x50, v0
	v_max_i32_e32 v2, 0xffffffa8, v12
	v_mul_lo_u32 v192, v0, s27
	v_add_u32_e32 v2, 0x58, v2
	v_lshl_add_u64 v[0:1], v[8:9], 0, v[192:193]
	v_mul_lo_u32 v192, v2, s27
	v_lshl_add_u64 v[2:3], v[8:9], 0, v[192:193]
	global_load_dwordx4 v[40:43], v[0:1], off
	global_load_dwordx4 v[44:47], v[2:3], off
	v_max_i32_e32 v0, 0xffffffa0, v12
	v_add_u32_e32 v0, 0x60, v0
	v_max_i32_e32 v2, 0xffffff98, v12
	v_mul_lo_u32 v192, v0, s27
	v_add_u32_e32 v2, 0x68, v2
	v_lshl_add_u64 v[0:1], v[8:9], 0, v[192:193]
	v_mul_lo_u32 v192, v2, s27
	v_lshl_add_u64 v[2:3], v[8:9], 0, v[192:193]
	global_load_dwordx4 v[16:19], v[0:1], off
	global_load_dwordx4 v[20:23], v[2:3], off
	v_max_i32_e32 v0, 0xffffff90, v12
	v_add_u32_e32 v0, 0x70, v0
	v_max_i32_e32 v2, 0xffffff88, v12
	v_mul_lo_u32 v192, v0, s27
	v_add_u32_e32 v2, 0x78, v2
	v_lshl_add_u64 v[0:1], v[8:9], 0, v[192:193]
	v_mul_lo_u32 v192, v2, s27
	v_lshl_add_u64 v[2:3], v[8:9], 0, v[192:193]
	global_load_dwordx4 v[24:27], v[0:1], off
	global_load_dwordx4 v[28:31], v[2:3], off
	v_max_i32_e32 v0, 0xffffff80, v12
	v_add_u32_e32 v0, 0x80, v0
	v_max_i32_e32 v2, 0xffffff78, v12
	v_mul_lo_u32 v192, v0, s27
	v_add_u32_e32 v2, 0x88, v2
	v_add_u32_e32 v10, s24, v139
	v_lshl_add_u64 v[0:1], v[8:9], 0, v[192:193]
	v_mul_lo_u32 v192, v2, s27
	v_max_i32_e32 v10, 0, v10
	v_max_i32_e32 v12, 0xffffff68, v12
	v_lshl_add_u64 v[4:5], v[8:9], 0, v[192:193]
	v_mul_lo_u32 v192, s27, v10
	v_add_u32_e32 v12, 0x98, v12
	v_lshl_add_u64 v[10:11], v[8:9], 0, v[192:193]
	v_mul_lo_u32 v192, v12, s27
	v_lshl_add_u64 v[12:13], v[8:9], 0, v[192:193]
	global_load_dwordx4 v[0:3], v[0:1], off
	s_nop 0
	global_load_dwordx4 v[4:7], v[4:5], off
	s_nop 0
	global_load_dwordx4 v[8:11], v[10:11], off
	s_nop 0
	global_load_dwordx4 v[12:15], v[12:13], off
	s_waitcnt vmcnt(36)
	ds_write_b128 v143, v[84:87] offset:2240
	ds_write_b128 v143, v[80:83] offset:3392
	ds_read_b128 v[84:87], v207 offset:2240
	ds_read_b128 v[80:83], v207 offset:2304
	ds_write_b128 v206, v[146:149] offset:2240
	ds_write_b128 v206, v[150:153] offset:2816
	ds_write_b128 v206, v[154:157] offset:3392
	ds_write_b128 v206, v[158:161] offset:3968
	ds_read_b128 v[146:149], v207 offset:2240
	ds_read_b128 v[150:153], v207 offset:2304
	ds_read_b128 v[154:157], v207 offset:4544
	ds_read_b128 v[158:161], v207 offset:4608
	s_waitcnt lgkmcnt(0)
	s_waitcnt vmcnt(39)
	v_mfma_f32_16x16x32_bf16 v[146:149], v[146:149], v[84:87], 0
	s_mulk_i32 s26, 0x2c0
	v_add_u32_e32 v186, s26, v135
	ds_read2_b32 v[182:183], v186 offset0:173 offset1:176
	s_waitcnt vmcnt(38)
	v_mfma_f32_16x16x32_bf16 v[146:149], v[150:153], v[80:83], v[146:149]
	s_waitcnt vmcnt(37)
	v_mfma_f32_16x16x32_bf16 v[150:153], v[154:157], v[84:87], 0
	s_waitcnt vmcnt(36)
	v_mfma_f32_16x16x32_bf16 v[154:157], v[158:161], v[80:83], v[150:153]
	s_waitcnt lgkmcnt(0)
	s_nop 2
	v_fmamk_f32 v146, v146, 0x3e000000, v183
	v_fmac_f32_e32 v182, 0x3e000000, v149
	v_cndmask_b32_e64 v146, v237, v146, s[38:39]
	s_waitcnt vmcnt(32)
	ds_write_b128 v206, v[162:165] offset:2240
	ds_write_b128 v206, v[166:169] offset:2816
	ds_write_b128 v206, v[170:173] offset:3392
	ds_write_b128 v206, v[174:177] offset:3968
	ds_read_b128 v[162:165], v207 offset:2240
	ds_read_b128 v[166:169], v207 offset:2304
	ds_read_b128 v[170:173], v207 offset:4544
	ds_read_b128 v[174:177], v207 offset:4608
	s_waitcnt lgkmcnt(0)
	s_waitcnt vmcnt(35)
	v_mfma_f32_16x16x32_bf16 v[150:153], v[162:165], v[84:87], 0
	ds_read2_b32 v[162:163], v186 offset0:174 offset1:175
	v_mov_b32_e32 v164, v147
	v_mov_b32_e32 v165, v148
	s_waitcnt vmcnt(34)
	v_mfma_f32_16x16x32_bf16 v[158:161], v[166:169], v[80:83], v[150:153]
	ds_read2_b32 v[184:185], v186 offset0:169 offset1:170
	s_nop 1
	ds_read2_b32 v[150:151], v186 offset0:171 offset1:172
	s_waitcnt lgkmcnt(2)
	v_pk_fma_f32 v[152:153], v[164:165], s[80:81], v[162:163] op_sel:[0,0,1] op_sel_hi:[1,0,0]
	v_cndmask_b32_e64 v149, v237, v182, s[46:47]
	s_waitcnt vmcnt(33)
	v_mfma_f32_16x16x32_bf16 v[162:165], v[170:173], v[84:87], 0
	s_waitcnt lgkmcnt(1)
	v_fmac_f32_e32 v184, 0x3e000000, v157
	s_waitcnt lgkmcnt(0)
	v_pk_fma_f32 v[150:151], v[154:155], s[80:81], v[150:151] op_sel:[0,0,1] op_sel_hi:[1,0,0]
	v_cndmask_b32_e64 v147, v237, v153, s[40:41]
	s_waitcnt vmcnt(28)
	ds_write_b128 v206, v[178:181] offset:2240
	ds_write_b128 v206, v[128:131] offset:2816
	ds_write_b128 v206, v[124:127] offset:3392
	ds_write_b128 v206, v[120:123] offset:3968
	ds_read_b128 v[178:181], v207 offset:2240
	ds_read_b128 v[128:131], v207 offset:2304
	ds_read_b128 v[124:127], v207 offset:4544
	ds_read_b128 v[120:123], v207 offset:4608
	s_waitcnt lgkmcnt(0)
	s_waitcnt vmcnt(31)
	v_mfma_f32_16x16x32_bf16 v[166:169], v[178:181], v[84:87], 0
	v_cndmask_b32_e64 v148, v237, v151, s[50:51]
	v_cndmask_b32_e64 v151, v237, v150, s[44:45]
	v_fmamk_f32 v150, v156, 0x3e000000, v185
	v_mfma_f32_16x16x32_bf16 v[162:165], v[174:177], v[80:83], v[162:165]
	v_cndmask_b32_e64 v152, v237, v152, s[42:43]
	v_cndmask_b32_e64 v150, v237, v150, s[48:49]
	s_waitcnt vmcnt(30)
; #define LAS __attribute__((address_space(3)))
; __device__ __forceinline__ f32x4 mfma16(bf16x8 a, bf16x8 b, f32x4 c) { return __builtin_amdgcn_mfma_f32_16x16x32_bf16(a, b, c, 0, 0, 0); }
; #define SBAR() __builtin_amdgcn_sched_barrier(0)
; #define SBAR() __builtin_amdgcn_sched_barrier(0)
; __device__ __forceinline__ void attnA_unit(const Ctx& C, int unit) {
;     ...
;         f32x4 S[10];
; #pragma unroll
;         for (int kt = 0; kt < 10; ++kt) { f32x4 a = mfma16(kf[kt][0], q0, (f32x4){0.f, 0.f, 0.f, 0.f}); S[kt] = mfma16(kf[kt][1], q1, a); }
;         const LAS float* tb = biasT + grp * 176 + 16 + L - 159;
;         const int kneg = kbase + 8 * g;
;         const bool anyneg = kbase < 0;
;         float tv[40];
; #pragma unroll
;         for (int kt = 0; kt < 10; ++kt)
; #pragma unroll
;             for (int jj = 0; jj < 4; ++jj) tv[4 * kt + jj] = tb[159 - (32 * (kt >> 1) + 4 * (kt & 1) + jj)];
;         SBAR();
;         float mx = NEGF;
; #pragma unroll
;         for (int kt = 0; kt < 10; ++kt)
; #pragma unroll
;             for (int jj = 0; jj < 4; ++jj) {
;                 const int c = 32 * (kt >> 1) + 4 * (kt & 1) + jj;
;                 float v = S[kt][jj] * 0.125f + tv[4 * kt + jj];
;                 if ((kt >> 1) == 0) v = (L - c <= 128) ? v : NEGF;
;                 if ((kt >> 1) == 4) v = (L - c >= 0) ? v : NEGF;
;                 S[kt][jj] = v;
;             }
;         if (anyneg) {
	v_mfma_f32_16x16x32_bf16 v[154:157], v[128:131], v[80:83], v[166:169]
	ds_read2_b32 v[130:131], v186 offset0:143 offset1:144
	ds_read2_b32 v[170:171], v186 offset0:141 offset1:142
	ds_read2_b32 v[172:173], v186 offset0:139 offset1:140
	ds_read2_b32 v[174:175], v186 offset0:137 offset1:138
	v_cndmask_b32_e64 v128, v237, v184, s[52:53]
	s_waitcnt vmcnt(29)
	v_mfma_f32_16x16x32_bf16 v[166:169], v[124:127], v[84:87], 0
	s_waitcnt lgkmcnt(3)
	v_pk_fma_f32 v[126:127], v[158:159], s[80:81], v[130:131] op_sel:[0,0,1] op_sel_hi:[1,0,0]
	s_waitcnt lgkmcnt(2)
	v_pk_fma_f32 v[124:125], v[160:161], s[80:81], v[170:171] op_sel:[0,0,1] op_sel_hi:[1,0,0]
	ds_read2_b32 v[130:131], v186 offset0:111 offset1:112
	s_waitcnt vmcnt(28)
	v_mfma_f32_16x16x32_bf16 v[158:161], v[120:123], v[80:83], v[166:169]
	s_waitcnt lgkmcnt(2)
	v_pk_fma_f32 v[122:123], v[162:163], s[80:81], v[172:173] op_sel:[0,0,1] op_sel_hi:[1,0,0]
	s_waitcnt lgkmcnt(1)
	v_pk_fma_f32 v[120:121], v[164:165], s[80:81], v[174:175] op_sel:[0,0,1] op_sel_hi:[1,0,0]
	s_waitcnt vmcnt(24)
	ds_write_b128 v206, v[116:119] offset:2240
	ds_write_b128 v206, v[112:115] offset:2816
	ds_write_b128 v206, v[108:111] offset:3392
	ds_write_b128 v206, v[100:103] offset:3968
	ds_read_b128 v[116:119], v207 offset:2240
	ds_read_b128 v[112:115], v207 offset:2304
	ds_read_b128 v[108:111], v207 offset:4544
	ds_read_b128 v[100:103], v207 offset:4608
	s_waitcnt lgkmcnt(0)
	s_waitcnt vmcnt(27)
	v_mfma_f32_16x16x32_bf16 v[162:165], v[116:119], v[84:87], 0
	ds_read2_b32 v[116:117], v186 offset0:109 offset1:110
	ds_read2_b32 v[166:167], v186 offset0:107 offset1:108
	ds_read2_b32 v[168:169], v186 offset0:105 offset1:106
	s_waitcnt lgkmcnt(3)
	v_pk_fma_f32 v[118:119], v[154:155], s[80:81], v[130:131] op_sel:[0,0,1] op_sel_hi:[1,0,0]
	s_waitcnt lgkmcnt(2)
	v_pk_fma_f32 v[116:117], v[156:157], s[80:81], v[116:117] op_sel:[0,0,1] op_sel_hi:[1,0,0]
	s_waitcnt vmcnt(25)
	v_mfma_f32_16x16x32_bf16 v[108:111], v[108:111], v[84:87], 0
	v_mfma_f32_16x16x32_bf16 v[162:165], v[112:115], v[80:83], v[162:165]
	s_waitcnt lgkmcnt(1)
	v_pk_fma_f32 v[114:115], v[158:159], s[80:81], v[166:167] op_sel:[0,0,1] op_sel_hi:[1,0,0]
	s_waitcnt lgkmcnt(0)
	v_pk_fma_f32 v[112:113], v[160:161], s[80:81], v[168:169] op_sel:[0,0,1] op_sel_hi:[1,0,0]
	ds_read2_b32 v[130:131], v186 offset0:79 offset1:80
	ds_read2_b32 v[158:159], v186 offset0:77 offset1:78
	ds_read2_b32 v[160:161], v186 offset0:75 offset1:76
	ds_read2_b32 v[166:167], v186 offset0:73 offset1:74
	s_waitcnt vmcnt(24)
	v_mfma_f32_16x16x32_bf16 v[154:157], v[100:103], v[80:83], v[108:111]
	s_waitcnt vmcnt(20)
	ds_write_b128 v206, v[104:107] offset:2240
	ds_write_b128 v206, v[96:99] offset:2816
	ds_write_b128 v206, v[92:95] offset:3392
	ds_write_b128 v206, v[88:91] offset:3968
	ds_read_b128 v[104:107], v207 offset:2240
	ds_read_b128 v[96:99], v207 offset:2304
	ds_read_b128 v[92:95], v207 offset:4544
	ds_read_b128 v[88:91], v207 offset:4608
	s_waitcnt lgkmcnt(0)
	s_waitcnt vmcnt(23)
	v_mfma_f32_16x16x32_bf16 v[104:107], v[104:107], v[84:87], 0
	s_waitcnt lgkmcnt(3)
	v_pk_fma_f32 v[110:111], v[162:163], s[80:81], v[130:131] op_sel:[0,0,1] op_sel_hi:[1,0,0]
	s_waitcnt lgkmcnt(1)
	s_nop 2
	v_pk_fma_f32 v[102:103], v[154:155], s[80:81], v[160:161] op_sel:[0,0,1] op_sel_hi:[1,0,0]
	ds_read2_b32 v[130:131], v186 offset0:47 offset1:48
	ds_read2_b32 v[154:155], v186 offset0:45 offset1:46
	s_waitcnt vmcnt(22)
	v_mfma_f32_16x16x32_bf16 v[96:99], v[96:99], v[80:83], v[104:107]
	v_fma_f32 v108, v164, s80, v159
	v_fma_f32 v109, v165, s80, v158
	s_waitcnt lgkmcnt(2)
	v_pk_fma_f32 v[100:101], v[156:157], s[80:81], v[166:167] op_sel:[0,0,1] op_sel_hi:[1,0,0]
	s_waitcnt vmcnt(21)
	v_mfma_f32_16x16x32_bf16 v[92:95], v[92:95], v[84:87], 0
	s_waitcnt vmcnt(20)
	v_mfma_f32_16x16x32_bf16 v[86:89], v[88:91], v[80:83], v[92:95]
	s_waitcnt lgkmcnt(1)
	v_pk_fma_f32 v[104:105], v[96:97], s[80:81], v[130:131] op_sel:[0,0,1] op_sel_hi:[1,0,0]
	s_waitcnt lgkmcnt(0)
	v_pk_fma_f32 v[98:99], v[98:99], s[80:81], v[154:155] op_sel:[0,0,1] op_sel_hi:[1,0,0]
	v_cndmask_b32_e64 v96, v105, v237, s[38:39]
	v_cndmask_b32_e64 v97, v104, v237, s[54:55]
	ds_read2_b32 v[104:105], v186 offset0:43 offset1:44
	v_cndmask_b32_e64 v84, v99, v237, s[40:41]
	v_cndmask_b32_e64 v85, v98, v237, s[42:43]
	ds_read2_b32 v[98:99], v186 offset0:41 offset1:42
	s_waitcnt lgkmcnt(1)
	v_pk_fma_f32 v[80:81], v[86:87], s[80:81], v[104:105] op_sel:[0,0,1] op_sel_hi:[1,0,0]
	s_nop 0
	v_cndmask_b32_e64 v82, v81, v237, s[44:45]
	v_cndmask_b32_e64 v83, v80, v237, s[46:47]
	s_waitcnt lgkmcnt(0)
	v_pk_fma_f32 v[86:87], v[88:89], s[80:81], v[98:99] op_sel:[0,0,1] op_sel_hi:[1,0,0]
	s_cmpk_gt_i32 s24, 0x8f
	v_cndmask_b32_e64 v80, v87, v237, s[48:49]
	v_cndmask_b32_e64 v86, v86, v237, s[50:51]
	s_cbranch_scc1 .LBB0_567
; __device__ __forceinline__ void attnA_unit(const Ctx& C, int unit) {
;     ...
;         if (anyneg) {
; #pragma unroll
;             for (int kt = 0; kt < 10; ++kt)
; #pragma unroll
;                 for (int jj = 0; jj < 4; ++jj) { const int c = 32 * (kt >> 1) + 4 * (kt & 1) + jj; S[kt][jj] = (kneg + c >= 0) ? S[kt][jj] : NEGF; }
;         }
	v_add_u32_e32 v81, s25, v134
	v_cmp_lt_i32_e64 s[56:57], -1, v81
	s_movk_i32 s24, 0xffdf
	s_nop 0
	v_cndmask_b32_e64 v146, v237, v146, s[56:57]
	v_cmp_lt_i32_e64 s[56:57], -2, v81
	s_nop 1
	v_cndmask_b32_e64 v152, v237, v152, s[56:57]
	v_cmp_lt_i32_e64 s[56:57], -3, v81
	s_nop 1
	v_cndmask_b32_e64 v147, v237, v147, s[56:57]
	v_cmp_lt_i32_e64 s[56:57], -4, v81
	s_nop 1
	v_cndmask_b32_e64 v149, v237, v149, s[56:57]
	v_cmp_lt_i32_e64 s[56:57], -5, v81
	s_nop 1
	v_cndmask_b32_e64 v151, v237, v151, s[56:57]
	v_cmp_lt_i32_e64 s[56:57], -6, v81
	s_nop 1
	v_cndmask_b32_e64 v148, v237, v148, s[56:57]
	v_cmp_lt_i32_e64 s[56:57], -7, v81
	s_nop 1
	v_cndmask_b32_e64 v150, v237, v150, s[56:57]
	v_cmp_lt_i32_e64 s[56:57], -8, v81
	s_nop 1
	v_cndmask_b32_e64 v128, v237, v128, s[56:57]
	v_cmp_lt_i32_e64 s[56:57], s24, v81
	s_movk_i32 s24, 0xffde
	s_nop 0
	v_cndmask_b32_e64 v126, v237, v126, s[56:57]
	v_cmp_lt_i32_e64 s[56:57], s24, v81
	s_movk_i32 s24, 0xffdd
	s_nop 0
	v_cndmask_b32_e64 v127, v237, v127, s[56:57]
	v_cmp_lt_i32_e64 s[56:57], s24, v81
	s_movk_i32 s24, 0xffdc
	s_nop 0
	v_cndmask_b32_e64 v124, v237, v124, s[56:57]
	v_cmp_lt_i32_e64 s[56:57], s24, v81
	s_movk_i32 s24, 0xffdb
	s_nop 0
	v_cndmask_b32_e64 v125, v237, v125, s[56:57]
	v_cmp_lt_i32_e64 s[56:57], s24, v81
	s_movk_i32 s24, 0xffda
	s_nop 0
	v_cndmask_b32_e64 v122, v237, v122, s[56:57]
	v_cmp_lt_i32_e64 s[56:57], s24, v81
	s_movk_i32 s24, 0xffd9
	s_nop 0
	v_cndmask_b32_e64 v123, v237, v123, s[56:57]
	v_cmp_lt_i32_e64 s[56:57], s24, v81
	s_movk_i32 s24, 0xffd8
	s_nop 0
	v_cndmask_b32_e64 v120, v237, v120, s[56:57]
	v_cmp_lt_i32_e64 s[56:57], s24, v81
	s_movk_i32 s24, 0xffbf
	s_nop 0
	v_cndmask_b32_e64 v121, v237, v121, s[56:57]
	v_cmp_lt_i32_e64 s[56:57], s24, v81
	s_movk_i32 s24, 0xffbe
	s_nop 0
	v_cndmask_b32_e64 v118, v237, v118, s[56:57]
	v_cmp_lt_i32_e64 s[56:57], s24, v81
	s_movk_i32 s24, 0xffbd
	s_nop 0
	v_cndmask_b32_e64 v119, v237, v119, s[56:57]
	v_cmp_lt_i32_e64 s[56:57], s24, v81
	s_movk_i32 s24, 0xffbc
	s_nop 0
	v_cndmask_b32_e64 v116, v237, v116, s[56:57]
	v_cmp_lt_i32_e64 s[56:57], s24, v81
	s_movk_i32 s24, 0xffbb
	s_nop 0
	v_cndmask_b32_e64 v117, v237, v117, s[56:57]
	v_cmp_lt_i32_e64 s[56:57], s24, v81
	s_movk_i32 s24, 0xffba
	s_nop 0
	v_cndmask_b32_e64 v114, v237, v114, s[56:57]
	v_cmp_lt_i32_e64 s[56:57], s24, v81
	s_movk_i32 s24, 0xffb9
	s_nop 0
	v_cndmask_b32_e64 v115, v237, v115, s[56:57]
	v_cmp_lt_i32_e64 s[56:57], s24, v81
	s_movk_i32 s24, 0xffb8
	s_nop 0
	v_cndmask_b32_e64 v112, v237, v112, s[56:57]
	v_cmp_lt_i32_e64 s[56:57], s24, v81
	s_movk_i32 s24, 0xff9f
	s_nop 0
	v_cndmask_b32_e64 v113, v237, v113, s[56:57]
	v_cmp_lt_i32_e64 s[56:57], s24, v81
	s_movk_i32 s24, 0xff9e
	s_nop 0
	v_cndmask_b32_e64 v110, v237, v110, s[56:57]
	v_cmp_lt_i32_e64 s[56:57], s24, v81
	s_movk_i32 s24, 0xff9d
	s_nop 0
	v_cndmask_b32_e64 v111, v237, v111, s[56:57]
	v_cmp_lt_i32_e64 s[56:57], s24, v81
	s_movk_i32 s24, 0xff9c
	s_nop 0
	v_cndmask_b32_e64 v108, v237, v108, s[56:57]
	v_cmp_lt_i32_e64 s[56:57], s24, v81
	s_movk_i32 s24, 0xff9b
	s_nop 0
	v_cndmask_b32_e64 v109, v237, v109, s[56:57]
	v_cmp_lt_i32_e64 s[56:57], s24, v81
	s_movk_i32 s24, 0xff9a
	s_nop 0
	v_cndmask_b32_e64 v102, v237, v102, s[56:57]
	v_cmp_lt_i32_e64 s[56:57], s24, v81
	s_movk_i32 s24, 0xff99
	s_nop 0
	v_cndmask_b32_e64 v103, v237, v103, s[56:57]
	v_cmp_lt_i32_e64 s[56:57], s24, v81
	s_movk_i32 s24, 0xff98
	s_nop 0
	v_cndmask_b32_e64 v100, v237, v100, s[56:57]
	v_cmp_lt_i32_e64 s[56:57], s24, v81
	s_movk_i32 s24, 0xff7f
	s_nop 0
	v_cndmask_b32_e64 v101, v237, v101, s[56:57]
	v_cmp_lt_i32_e64 s[56:57], s24, v81
	s_movk_i32 s24, 0xff7e
	s_nop 0
	v_cndmask_b32_e64 v97, v237, v97, s[56:57]
	v_cmp_lt_i32_e64 s[56:57], s24, v81
	s_movk_i32 s24, 0xff7d
	s_nop 0
	v_cndmask_b32_e64 v96, v237, v96, s[56:57]
	v_cmp_lt_i32_e64 s[56:57], s24, v81
	s_movk_i32 s24, 0xff7b
	s_nop 0
	v_cndmask_b32_e64 v85, v237, v85, s[56:57]
	v_cmp_lt_i32_e64 s[56:57], s6, v81
	s_nop 1
	v_cndmask_b32_e64 v84, v237, v84, s[56:57]
	v_cmp_lt_i32_e64 s[56:57], s24, v81
	s_movk_i32 s24, 0xff7a
	s_nop 0
	v_cndmask_b32_e64 v83, v237, v83, s[56:57]
	v_cmp_lt_i32_e64 s[56:57], s24, v81
	s_movk_i32 s24, 0xff79
	s_nop 0
	v_cndmask_b32_e64 v82, v237, v82, s[56:57]
	v_cmp_lt_i32_e64 s[56:57], s24, v81
	s_movk_i32 s24, 0xff78
	s_nop 0
	v_cndmask_b32_e64 v86, v237, v86, s[56:57]
	v_cmp_lt_i32_e64 s[56:57], s24, v81
	s_nop 1
	v_cndmask_b32_e64 v80, v237, v80, s[56:57]
